# P1 proj stores write-through (sc0 sc1): less dirty L2 data to write back at the grid barrier
# speedup vs baseline: 1.0574x; 1.0007x over previous
.LBB0_166:
	s_add_u32 s20, s18, 0xfffc0080
	s_addc_u32 s21, s19, -1
	s_add_i32 s42, 0, 0x10000
	v_add_u32_e32 v140, s42, v143
	ds_read_b128 v[146:149], v140
	ds_read_b128 v[150:153], v140 offset:1024
	ds_read_b128 v[168:171], v140 offset:2048
	ds_read_b128 v[172:175], v140 offset:3072
	s_cmp_eq_u32 s41, 12
	s_cselect_b32 s23, s9, s21
	s_cselect_b32 s22, s37, s20
	s_cselect_b32 s21, s7, s40
	s_cselect_b32 s20, s38, s39
	v_lshl_add_u64 v[140:141], s[18:19], 0, v[136:137]
	s_add_i32 m0, s15, 0xc000
	ds_read_b128 v[176:179], v145
	ds_read_b128 v[180:183], v145 offset:1024
	ds_read_b128 v[184:187], v145 offset:2048
	ds_read_b128 v[188:191], v145 offset:3072
	ds_read_b128 v[192:195], v145 offset:4096
	ds_read_b128 v[196:199], v145 offset:5120
	ds_read_b128 v[200:203], v145 offset:6144
	ds_read_b128 v[204:207], v145 offset:7168
	global_load_lds_dwordx4 v[140:141], off
	v_lshl_add_u64 v[140:141], s[18:19], 0, v[138:139]
	s_add_i32 m0, s15, 0xe000
	s_nop 0
	global_load_lds_dwordx4 v[140:141], off
	s_waitcnt lgkmcnt(8)
	s_barrier
	s_waitcnt lgkmcnt(0)
	s_setprio 1
	s_waitcnt lgkmcnt(0)
	v_mfma_f32_16x16x32_bf16 v[128:131], v[146:149], v[176:179], v[128:131]
	v_mfma_f32_16x16x32_bf16 v[124:127], v[168:171], v[176:179], v[124:127]
	v_mfma_f32_16x16x32_bf16 v[116:119], v[146:149], v[184:187], v[116:119]
	v_mfma_f32_16x16x32_bf16 v[108:111], v[168:171], v[184:187], v[108:111]
	v_mfma_f32_16x16x32_bf16 v[100:103], v[146:149], v[192:195], v[100:103]
	v_mfma_f32_16x16x32_bf16 v[92:95], v[168:171], v[192:195], v[92:95]
	v_mfma_f32_16x16x32_bf16 v[84:87], v[146:149], v[200:203], v[84:87]
	v_mfma_f32_16x16x32_bf16 v[76:79], v[168:171], v[200:203], v[76:79]
	v_mfma_f32_16x16x32_bf16 v[128:131], v[150:153], v[180:183], v[128:131]
	v_mfma_f32_16x16x32_bf16 v[124:127], v[172:175], v[180:183], v[124:127]
	v_mfma_f32_16x16x32_bf16 v[116:119], v[150:153], v[188:191], v[116:119]
	v_mfma_f32_16x16x32_bf16 v[108:111], v[172:175], v[188:191], v[108:111]
	v_mfma_f32_16x16x32_bf16 v[100:103], v[150:153], v[196:199], v[100:103]
	v_mfma_f32_16x16x32_bf16 v[92:95], v[172:175], v[196:199], v[92:95]
	v_mfma_f32_16x16x32_bf16 v[84:87], v[150:153], v[204:207], v[84:87]
	v_mfma_f32_16x16x32_bf16 v[76:79], v[172:175], v[204:207], v[76:79]
	s_setprio 0
	s_barrier
	s_add_i32 s44, 0, 0x14000
	v_add_u32_e32 v140, s44, v143
	s_add_i32 s42, s42, s29
	ds_read_b128 v[208:211], v140
	ds_read_b128 v[212:215], v140 offset:1024
	ds_read_b128 v[216:219], v140 offset:2048
	ds_read_b128 v[220:223], v140 offset:3072
	v_lshl_add_u64 v[140:141], s[20:21], 0, v[2:3]
	s_mov_b32 m0, s42
	v_lshl_add_u64 v[154:155], s[20:21], 0, v[0:1]
	global_load_lds_dwordx4 v[140:141], off
	s_add_i32 m0, s42, 0x2000
	s_nop 0
	global_load_lds_dwordx4 v[154:155], off
	s_barrier
	s_waitcnt lgkmcnt(0)
	s_setprio 1
	s_waitcnt lgkmcnt(0)
	v_mfma_f32_16x16x32_bf16 v[120:123], v[208:211], v[176:179], v[120:123]
	v_mfma_f32_16x16x32_bf16 v[112:115], v[216:219], v[176:179], v[112:115]
	v_mfma_f32_16x16x32_bf16 v[104:107], v[208:211], v[184:187], v[104:107]
	v_mfma_f32_16x16x32_bf16 v[96:99], v[216:219], v[184:187], v[96:99]
	v_mfma_f32_16x16x32_bf16 v[88:91], v[208:211], v[192:195], v[88:91]
	v_mfma_f32_16x16x32_bf16 v[80:83], v[216:219], v[192:195], v[80:83]
	v_mfma_f32_16x16x32_bf16 v[72:75], v[208:211], v[200:203], v[72:75]
	v_mfma_f32_16x16x32_bf16 v[68:71], v[216:219], v[200:203], v[68:71]
	v_mfma_f32_16x16x32_bf16 v[120:123], v[212:215], v[180:183], v[120:123]
	v_mfma_f32_16x16x32_bf16 v[112:115], v[220:223], v[180:183], v[112:115]
	v_mfma_f32_16x16x32_bf16 v[104:107], v[212:215], v[188:191], v[104:107]
	v_mfma_f32_16x16x32_bf16 v[96:99], v[220:223], v[188:191], v[96:99]
	v_mfma_f32_16x16x32_bf16 v[88:91], v[212:215], v[196:199], v[88:91]
	v_mfma_f32_16x16x32_bf16 v[80:83], v[220:223], v[196:199], v[80:83]
	v_mfma_f32_16x16x32_bf16 v[72:75], v[212:215], v[204:207], v[72:75]
	v_mfma_f32_16x16x32_bf16 v[68:71], v[220:223], v[204:207], v[68:71]
	s_setprio 0
	s_mov_b32 m0, s15
	v_lshl_add_u64 v[224:225], s[22:23], 0, v[134:135]
	s_barrier
	ds_read_b128 v[176:179], v145 offset:16384
	ds_read_b128 v[180:183], v145 offset:17408
	ds_read_b128 v[184:187], v145 offset:18432
	ds_read_b128 v[188:191], v145 offset:19456
	ds_read_b128 v[192:195], v145 offset:20480
	ds_read_b128 v[196:199], v145 offset:21504
	ds_read_b128 v[200:203], v145 offset:22528
	ds_read_b128 v[204:207], v145 offset:23552
	global_load_lds_dwordx4 v[224:225], off
	v_lshl_add_u64 v[226:227], s[22:23], 0, v[132:133]
	s_mov_b32 m0, s17
	s_nop 0
	global_load_lds_dwordx4 v[226:227], off
	s_barrier
	s_waitcnt lgkmcnt(0)
	s_setprio 1
	s_waitcnt lgkmcnt(0)
	v_mfma_f32_16x16x32_bf16 v[64:67], v[146:149], v[176:179], v[64:67]
	v_mfma_f32_16x16x32_bf16 v[60:63], v[168:171], v[176:179], v[60:63]
	v_mfma_f32_16x16x32_bf16 v[52:55], v[146:149], v[184:187], v[52:55]
	v_mfma_f32_16x16x32_bf16 v[44:47], v[168:171], v[184:187], v[44:47]
	v_mfma_f32_16x16x32_bf16 v[36:39], v[146:149], v[192:195], v[36:39]
	v_mfma_f32_16x16x32_bf16 v[28:31], v[168:171], v[192:195], v[28:31]
	v_mfma_f32_16x16x32_bf16 v[20:23], v[146:149], v[200:203], v[20:23]
	v_mfma_f32_16x16x32_bf16 v[12:15], v[168:171], v[200:203], v[12:15]
	v_mfma_f32_16x16x32_bf16 v[64:67], v[150:153], v[180:183], v[64:67]
	v_mfma_f32_16x16x32_bf16 v[60:63], v[172:175], v[180:183], v[60:63]
	v_mfma_f32_16x16x32_bf16 v[52:55], v[150:153], v[188:191], v[52:55]
	v_mfma_f32_16x16x32_bf16 v[44:47], v[172:175], v[188:191], v[44:47]
	v_mfma_f32_16x16x32_bf16 v[36:39], v[150:153], v[196:199], v[36:39]
	v_mfma_f32_16x16x32_bf16 v[28:31], v[172:175], v[196:199], v[28:31]
	v_mfma_f32_16x16x32_bf16 v[20:23], v[150:153], v[204:207], v[20:23]
	v_mfma_f32_16x16x32_bf16 v[12:15], v[172:175], v[204:207], v[12:15]
	s_setprio 0
	s_barrier
	s_add_u32 s42, s20, 0x40000
	s_addc_u32 s43, s21, 0
	s_add_i32 s44, s44, s29
	v_lshl_add_u64 v[146:147], s[42:43], 0, v[2:3]
	s_mov_b32 m0, s44
	s_nop 0
	global_load_lds_dwordx4 v[146:147], off
	v_lshl_add_u64 v[146:147], s[42:43], 0, v[0:1]
	s_add_i32 m0, s44, 0x2000
	s_nop 0
	global_load_lds_dwordx4 v[146:147], off
	s_waitcnt vmcnt(6)
	s_barrier
	s_setprio 1
	v_mfma_f32_16x16x32_bf16 v[56:59], v[208:211], v[176:179], v[56:59]
	v_mfma_f32_16x16x32_bf16 v[48:51], v[216:219], v[176:179], v[48:51]
	v_mfma_f32_16x16x32_bf16 v[40:43], v[208:211], v[184:187], v[40:43]
	v_mfma_f32_16x16x32_bf16 v[32:35], v[216:219], v[184:187], v[32:35]
	v_mfma_f32_16x16x32_bf16 v[24:27], v[208:211], v[192:195], v[24:27]
	v_mfma_f32_16x16x32_bf16 v[16:19], v[216:219], v[192:195], v[16:19]
	v_mfma_f32_16x16x32_bf16 v[8:11], v[208:211], v[200:203], v[8:11]
	v_mfma_f32_16x16x32_bf16 v[4:7], v[216:219], v[200:203], v[4:7]
	v_mfma_f32_16x16x32_bf16 v[56:59], v[212:215], v[180:183], v[56:59]
	v_mfma_f32_16x16x32_bf16 v[48:51], v[220:223], v[180:183], v[48:51]
	v_mfma_f32_16x16x32_bf16 v[40:43], v[212:215], v[188:191], v[40:43]
	v_mfma_f32_16x16x32_bf16 v[32:35], v[220:223], v[188:191], v[32:35]
	v_mfma_f32_16x16x32_bf16 v[24:27], v[212:215], v[196:199], v[24:27]
	v_mfma_f32_16x16x32_bf16 v[16:19], v[220:223], v[196:199], v[16:19]
	v_mfma_f32_16x16x32_bf16 v[8:11], v[212:215], v[204:207], v[8:11]
	v_mfma_f32_16x16x32_bf16 v[4:7], v[220:223], v[204:207], v[4:7]
	s_setprio 0
	s_add_i32 s42, 0, 0x18000
	v_add_u32_e32 v161, s42, v143
	s_barrier
	ds_read_b128 v[146:149], v161
	ds_read_b128 v[150:153], v161 offset:1024
	ds_read_b128 v[168:171], v161 offset:2048
	ds_read_b128 v[172:175], v161 offset:3072
	s_add_u32 s22, s22, 0x40000
	s_addc_u32 s23, s23, 0
	s_mov_b32 m0, s30
	v_lshl_add_u64 v[208:209], s[22:23], 0, v[134:135]
	ds_read_b128 v[176:179], v145 offset:32768
	ds_read_b128 v[180:183], v145 offset:33792
	ds_read_b128 v[184:187], v145 offset:34816
	ds_read_b128 v[188:191], v145 offset:35840
	ds_read_b128 v[192:195], v145 offset:36864
	ds_read_b128 v[196:199], v145 offset:37888
	ds_read_b128 v[200:203], v145 offset:38912
	ds_read_b128 v[204:207], v145 offset:39936
	global_load_lds_dwordx4 v[208:209], off
	v_lshl_add_u64 v[208:209], s[22:23], 0, v[132:133]
	s_mov_b32 m0, s31
	s_nop 0
	global_load_lds_dwordx4 v[208:209], off
	s_waitcnt lgkmcnt(8)
	s_barrier
	s_waitcnt lgkmcnt(0)
	s_setprio 1
	s_waitcnt lgkmcnt(0)
	v_mfma_f32_16x16x32_bf16 v[128:131], v[146:149], v[176:179], v[128:131]
	v_mfma_f32_16x16x32_bf16 v[124:127], v[168:171], v[176:179], v[124:127]
	v_mfma_f32_16x16x32_bf16 v[116:119], v[146:149], v[184:187], v[116:119]
	v_mfma_f32_16x16x32_bf16 v[108:111], v[168:171], v[184:187], v[108:111]
	v_mfma_f32_16x16x32_bf16 v[100:103], v[146:149], v[192:195], v[100:103]
	v_mfma_f32_16x16x32_bf16 v[92:95], v[168:171], v[192:195], v[92:95]
	v_mfma_f32_16x16x32_bf16 v[84:87], v[146:149], v[200:203], v[84:87]
	v_mfma_f32_16x16x32_bf16 v[76:79], v[168:171], v[200:203], v[76:79]
	v_mfma_f32_16x16x32_bf16 v[128:131], v[150:153], v[180:183], v[128:131]
	v_mfma_f32_16x16x32_bf16 v[124:127], v[172:175], v[180:183], v[124:127]
	v_mfma_f32_16x16x32_bf16 v[116:119], v[150:153], v[188:191], v[116:119]
	v_mfma_f32_16x16x32_bf16 v[108:111], v[172:175], v[188:191], v[108:111]
	v_mfma_f32_16x16x32_bf16 v[100:103], v[150:153], v[196:199], v[100:103]
	v_mfma_f32_16x16x32_bf16 v[92:95], v[172:175], v[196:199], v[92:95]
	v_mfma_f32_16x16x32_bf16 v[84:87], v[150:153], v[204:207], v[84:87]
	v_mfma_f32_16x16x32_bf16 v[76:79], v[172:175], v[204:207], v[76:79]
	s_setprio 0
	s_barrier
	s_add_i32 s22, 0, 0x1c000
	s_add_i32 s23, s42, s29
	v_add_u32_e32 v161, s22, v143
	v_lshl_add_u64 v[140:141], v[140:141], 0, s[94:95]
	s_mov_b32 m0, s23
	ds_read_b128 v[208:211], v161
	ds_read_b128 v[212:215], v161 offset:1024
	ds_read_b128 v[216:219], v161 offset:2048
	ds_read_b128 v[220:223], v161 offset:3072
	global_load_lds_dwordx4 v[140:141], off
	v_lshl_add_u64 v[140:141], v[154:155], 0, s[94:95]
	s_add_i32 m0, s23, 0x2000
	s_nop 0
	global_load_lds_dwordx4 v[140:141], off
	s_barrier
	s_waitcnt lgkmcnt(0)
	s_setprio 1
	s_waitcnt lgkmcnt(0)
	v_mfma_f32_16x16x32_bf16 v[120:123], v[208:211], v[176:179], v[120:123]
	v_mfma_f32_16x16x32_bf16 v[112:115], v[216:219], v[176:179], v[112:115]
	v_mfma_f32_16x16x32_bf16 v[104:107], v[208:211], v[184:187], v[104:107]
	v_mfma_f32_16x16x32_bf16 v[96:99], v[216:219], v[184:187], v[96:99]
	v_mfma_f32_16x16x32_bf16 v[88:91], v[208:211], v[192:195], v[88:91]
	v_mfma_f32_16x16x32_bf16 v[80:83], v[216:219], v[192:195], v[80:83]
	v_mfma_f32_16x16x32_bf16 v[72:75], v[208:211], v[200:203], v[72:75]
	v_mfma_f32_16x16x32_bf16 v[68:71], v[216:219], v[200:203], v[68:71]
	v_mfma_f32_16x16x32_bf16 v[120:123], v[212:215], v[180:183], v[120:123]
	v_mfma_f32_16x16x32_bf16 v[112:115], v[220:223], v[180:183], v[112:115]
	v_mfma_f32_16x16x32_bf16 v[104:107], v[212:215], v[188:191], v[104:107]
	v_mfma_f32_16x16x32_bf16 v[96:99], v[220:223], v[188:191], v[96:99]
	v_mfma_f32_16x16x32_bf16 v[88:91], v[212:215], v[196:199], v[88:91]
	v_mfma_f32_16x16x32_bf16 v[80:83], v[220:223], v[196:199], v[80:83]
	v_mfma_f32_16x16x32_bf16 v[72:75], v[212:215], v[204:207], v[72:75]
	v_mfma_f32_16x16x32_bf16 v[68:71], v[220:223], v[204:207], v[68:71]
	s_setprio 0
	s_mov_b32 m0, s34
	v_lshl_add_u64 v[140:141], v[224:225], 0, s[94:95]
	s_barrier
	ds_read_b128 v[176:179], v145 offset:49152
	ds_read_b128 v[180:183], v145 offset:50176
	ds_read_b128 v[184:187], v145 offset:51200
	ds_read_b128 v[188:191], v145 offset:52224
	ds_read_b128 v[192:195], v145 offset:53248
	ds_read_b128 v[196:199], v145 offset:54272
	ds_read_b128 v[200:203], v145 offset:55296
	ds_read_b128 v[204:207], v145 offset:56320
	global_load_lds_dwordx4 v[140:141], off
	v_lshl_add_u64 v[140:141], v[226:227], 0, s[94:95]
	s_mov_b32 m0, s35
	s_nop 0
	global_load_lds_dwordx4 v[140:141], off
	s_barrier
	s_waitcnt lgkmcnt(0)
	s_setprio 1
	s_waitcnt lgkmcnt(0)
	v_mfma_f32_16x16x32_bf16 v[64:67], v[146:149], v[176:179], v[64:67]
	v_mfma_f32_16x16x32_bf16 v[60:63], v[168:171], v[176:179], v[60:63]
	v_mfma_f32_16x16x32_bf16 v[52:55], v[146:149], v[184:187], v[52:55]
	v_mfma_f32_16x16x32_bf16 v[44:47], v[168:171], v[184:187], v[44:47]
	v_mfma_f32_16x16x32_bf16 v[36:39], v[146:149], v[192:195], v[36:39]
	v_mfma_f32_16x16x32_bf16 v[28:31], v[168:171], v[192:195], v[28:31]
	v_mfma_f32_16x16x32_bf16 v[20:23], v[146:149], v[200:203], v[20:23]
	v_mfma_f32_16x16x32_bf16 v[12:15], v[168:171], v[200:203], v[12:15]
	v_mfma_f32_16x16x32_bf16 v[64:67], v[150:153], v[180:183], v[64:67]
	v_mfma_f32_16x16x32_bf16 v[60:63], v[172:175], v[180:183], v[60:63]
	v_mfma_f32_16x16x32_bf16 v[52:55], v[150:153], v[188:191], v[52:55]
	v_mfma_f32_16x16x32_bf16 v[44:47], v[172:175], v[188:191], v[44:47]
	v_mfma_f32_16x16x32_bf16 v[36:39], v[150:153], v[196:199], v[36:39]
	v_mfma_f32_16x16x32_bf16 v[28:31], v[172:175], v[196:199], v[28:31]
	v_mfma_f32_16x16x32_bf16 v[20:23], v[150:153], v[204:207], v[20:23]
	v_mfma_f32_16x16x32_bf16 v[12:15], v[172:175], v[204:207], v[12:15]
	s_setprio 0
	s_barrier
	s_add_u32 s20, s20, 0x40080
	s_addc_u32 s21, s21, 0
	s_add_i32 s22, s22, s29
	v_lshl_add_u64 v[140:141], s[20:21], 0, v[2:3]
	s_mov_b32 m0, s22
	s_nop 0
	global_load_lds_dwordx4 v[140:141], off
	v_lshl_add_u64 v[140:141], s[20:21], 0, v[0:1]
	s_add_i32 m0, s22, 0x2000
	s_nop 0
	global_load_lds_dwordx4 v[140:141], off
	s_waitcnt vmcnt(6)
	s_barrier
	s_setprio 1
	v_mfma_f32_16x16x32_bf16 v[56:59], v[208:211], v[176:179], v[56:59]
	v_mfma_f32_16x16x32_bf16 v[48:51], v[216:219], v[176:179], v[48:51]
	v_mfma_f32_16x16x32_bf16 v[40:43], v[208:211], v[184:187], v[40:43]
	v_mfma_f32_16x16x32_bf16 v[32:35], v[216:219], v[184:187], v[32:35]
	v_mfma_f32_16x16x32_bf16 v[24:27], v[208:211], v[192:195], v[24:27]
	v_mfma_f32_16x16x32_bf16 v[16:19], v[216:219], v[192:195], v[16:19]
	v_mfma_f32_16x16x32_bf16 v[8:11], v[208:211], v[200:203], v[8:11]
	v_mfma_f32_16x16x32_bf16 v[4:7], v[216:219], v[200:203], v[4:7]
	v_mfma_f32_16x16x32_bf16 v[56:59], v[212:215], v[180:183], v[56:59]
	v_mfma_f32_16x16x32_bf16 v[48:51], v[220:223], v[180:183], v[48:51]
	v_mfma_f32_16x16x32_bf16 v[40:43], v[212:215], v[188:191], v[40:43]
	v_mfma_f32_16x16x32_bf16 v[32:35], v[220:223], v[188:191], v[32:35]
	v_mfma_f32_16x16x32_bf16 v[24:27], v[212:215], v[196:199], v[24:27]
	v_mfma_f32_16x16x32_bf16 v[16:19], v[220:223], v[196:199], v[16:19]
	v_mfma_f32_16x16x32_bf16 v[8:11], v[212:215], v[204:207], v[8:11]
	v_mfma_f32_16x16x32_bf16 v[4:7], v[220:223], v[204:207], v[4:7]
	s_setprio 0
	s_add_i32 s41, s41, 2
	s_add_u32 s18, s18, 0x100
	s_addc_u32 s19, s19, 0
	s_add_u32 s39, s39, 0x100
	s_addc_u32 s40, s40, 0
	s_cmp_gt_u32 s41, 13
	s_barrier
	s_cbranch_scc0 .LBB0_166
	v_lshl_or_b32 v140, s14, 8, v144
	v_ashrrev_i32_e32 v141, 31, v140
	v_lshl_add_u32 v150, s16, 8, v142
	v_lshl_add_u64 v[140:141], v[140:141], 1, s[2:3]
	v_mad_i64_i32 v[146:147], s[18:19], v150, s64, v[140:141]
	v_pk_add_f32 v[130:131], v[130:131], 0 op_sel_hi:[1,0]
	v_pk_add_f32 v[128:129], v[128:129], 0 op_sel_hi:[1,0]
	v_pk_add_f32 v[148:149], v[126:127], 0 op_sel_hi:[1,0]
	v_pk_add_f32 v[126:127], v[124:125], 0 op_sel_hi:[1,0]
	v_cvt_pk_bf16_f32 v124, v128, v129
	v_cvt_pk_bf16_f32 v125, v130, v131
	v_pk_add_f32 v[120:121], v[120:121], 0 op_sel_hi:[1,0]
	v_cvt_pk_bf16_f32 v126, v126, v127
	v_cvt_pk_bf16_f32 v127, v148, v149
	global_store_dwordx4 v[146:147], v[124:127], off sc0 sc1
	v_pk_add_f32 v[122:123], v[122:123], 0 op_sel_hi:[1,0]
	v_pk_add_f32 v[116:117], v[116:117], 0 op_sel_hi:[1,0]
	v_pk_add_f32 v[124:125], v[114:115], 0 op_sel_hi:[1,0]
	v_pk_add_f32 v[114:115], v[112:113], 0 op_sel_hi:[1,0]
	v_cvt_pk_bf16_f32 v112, v120, v121
	v_cvt_pk_bf16_f32 v113, v122, v123
	v_pk_add_f32 v[104:105], v[104:105], 0 op_sel_hi:[1,0]
	v_cvt_pk_bf16_f32 v114, v114, v115
	v_cvt_pk_bf16_f32 v115, v124, v125
	global_store_dwordx4 v[146:147], v[112:115], off offset:256 sc0 sc1
	v_pk_add_f32 v[106:107], v[106:107], 0 op_sel_hi:[1,0]
	v_pk_add_f32 v[100:101], v[100:101], 0 op_sel_hi:[1,0]
	v_or_b32_e32 v112, 16, v150
	v_mad_i64_i32 v[112:113], s[18:19], v112, s64, v[140:141]
	v_pk_add_f32 v[114:115], v[118:119], 0 op_sel_hi:[1,0]
	v_pk_add_f32 v[118:119], v[110:111], 0 op_sel_hi:[1,0]
	v_pk_add_f32 v[110:111], v[108:109], 0 op_sel_hi:[1,0]
	v_cvt_pk_bf16_f32 v108, v116, v117
	v_cvt_pk_bf16_f32 v109, v114, v115
	v_pk_add_f32 v[88:89], v[88:89], 0 op_sel_hi:[1,0]
	v_cvt_pk_bf16_f32 v110, v110, v111
	v_cvt_pk_bf16_f32 v111, v118, v119
	global_store_dwordx4 v[112:113], v[108:111], off sc0 sc1
	v_pk_add_f32 v[90:91], v[90:91], 0 op_sel_hi:[1,0]
	v_pk_add_f32 v[84:85], v[84:85], 0 op_sel_hi:[1,0]
	v_pk_add_f32 v[108:109], v[98:99], 0 op_sel_hi:[1,0]
	v_pk_add_f32 v[98:99], v[96:97], 0 op_sel_hi:[1,0]
	v_cvt_pk_bf16_f32 v96, v104, v105
	v_cvt_pk_bf16_f32 v97, v106, v107
	v_pk_add_f32 v[72:73], v[72:73], 0 op_sel_hi:[1,0]
	v_cvt_pk_bf16_f32 v98, v98, v99
	v_cvt_pk_bf16_f32 v99, v108, v109
	global_store_dwordx4 v[112:113], v[96:99], off offset:256 sc0 sc1
	v_pk_add_f32 v[74:75], v[74:75], 0 op_sel_hi:[1,0]
	v_pk_add_f32 v[66:67], v[66:67], 0 op_sel_hi:[1,0]
	v_or_b32_e32 v96, 32, v150
	v_mad_i64_i32 v[96:97], s[18:19], v96, s64, v[140:141]
	v_pk_add_f32 v[98:99], v[102:103], 0 op_sel_hi:[1,0]
	v_pk_add_f32 v[102:103], v[94:95], 0 op_sel_hi:[1,0]
	v_pk_add_f32 v[94:95], v[92:93], 0 op_sel_hi:[1,0]
	v_cvt_pk_bf16_f32 v92, v100, v101
	v_cvt_pk_bf16_f32 v93, v98, v99
	v_pk_add_f32 v[64:65], v[64:65], 0 op_sel_hi:[1,0]
	v_cvt_pk_bf16_f32 v94, v94, v95
	v_cvt_pk_bf16_f32 v95, v102, v103
	global_store_dwordx4 v[96:97], v[92:95], off sc0 sc1
	v_pk_add_f32 v[56:57], v[56:57], 0 op_sel_hi:[1,0]
	v_pk_add_f32 v[58:59], v[58:59], 0 op_sel_hi:[1,0]
	v_pk_add_f32 v[92:93], v[82:83], 0 op_sel_hi:[1,0]
	v_pk_add_f32 v[82:83], v[80:81], 0 op_sel_hi:[1,0]
	v_cvt_pk_bf16_f32 v80, v88, v89
	v_cvt_pk_bf16_f32 v81, v90, v91
	v_pk_add_f32 v[52:53], v[52:53], 0 op_sel_hi:[1,0]
	v_cvt_pk_bf16_f32 v82, v82, v83
	v_cvt_pk_bf16_f32 v83, v92, v93
	global_store_dwordx4 v[96:97], v[80:83], off offset:256 sc0 sc1
	v_pk_add_f32 v[40:41], v[40:41], 0 op_sel_hi:[1,0]
	v_pk_add_f32 v[42:43], v[42:43], 0 op_sel_hi:[1,0]
	v_or_b32_e32 v80, 48, v150
	v_mad_i64_i32 v[80:81], s[18:19], v80, s64, v[140:141]
	v_pk_add_f32 v[82:83], v[86:87], 0 op_sel_hi:[1,0]
	v_pk_add_f32 v[86:87], v[78:79], 0 op_sel_hi:[1,0]
	v_pk_add_f32 v[78:79], v[76:77], 0 op_sel_hi:[1,0]
	v_cvt_pk_bf16_f32 v76, v84, v85
	v_cvt_pk_bf16_f32 v77, v82, v83
	v_pk_add_f32 v[36:37], v[36:37], 0 op_sel_hi:[1,0]
	v_cvt_pk_bf16_f32 v78, v78, v79
	v_cvt_pk_bf16_f32 v79, v86, v87
	global_store_dwordx4 v[80:81], v[76:79], off sc0 sc1
	v_pk_add_f32 v[24:25], v[24:25], 0 op_sel_hi:[1,0]
	v_pk_add_f32 v[26:27], v[26:27], 0 op_sel_hi:[1,0]
	v_pk_add_f32 v[76:77], v[70:71], 0 op_sel_hi:[1,0]
	v_pk_add_f32 v[70:71], v[68:69], 0 op_sel_hi:[1,0]
	v_cvt_pk_bf16_f32 v68, v72, v73
	v_cvt_pk_bf16_f32 v69, v74, v75
	v_pk_add_f32 v[20:21], v[20:21], 0 op_sel_hi:[1,0]
	v_cvt_pk_bf16_f32 v70, v70, v71
	v_cvt_pk_bf16_f32 v71, v76, v77
	global_store_dwordx4 v[80:81], v[68:71], off offset:256 sc0 sc1
	s_and_b64 vcc, exec, s[4:5]
	s_mov_b32 s14, s6
	v_add_u32_e32 v68, 0x80, v150
	v_mad_i64_i32 v[68:69], s[18:19], v68, s64, v[140:141]
	v_pk_add_f32 v[70:71], v[62:63], 0 op_sel_hi:[1,0]
	v_pk_add_f32 v[62:63], v[60:61], 0 op_sel_hi:[1,0]
	v_cvt_pk_bf16_f32 v60, v64, v65
	v_cvt_pk_bf16_f32 v61, v66, v67
	s_mov_b32 s16, s8
	v_cvt_pk_bf16_f32 v62, v62, v63
	v_cvt_pk_bf16_f32 v63, v70, v71
	global_store_dwordx4 v[68:69], v[60:63], off sc0 sc1
	s_mov_b64 s[20:21], s[12:13]
	v_pk_add_f32 v[10:11], v[10:11], 0 op_sel_hi:[1,0]
	v_pk_add_f32 v[60:61], v[50:51], 0 op_sel_hi:[1,0]
	v_pk_add_f32 v[50:51], v[48:49], 0 op_sel_hi:[1,0]
	v_cvt_pk_bf16_f32 v48, v56, v57
	v_cvt_pk_bf16_f32 v49, v58, v59
	v_pk_add_f32 v[8:9], v[8:9], 0 op_sel_hi:[1,0]
	v_cvt_pk_bf16_f32 v50, v50, v51
	v_cvt_pk_bf16_f32 v51, v60, v61
	global_store_dwordx4 v[68:69], v[48:51], off offset:256 sc0 sc1
	s_nop 1
	v_add_u32_e32 v48, 0x90, v150
	v_mad_i64_i32 v[48:49], s[18:19], v48, s64, v[140:141]
	v_pk_add_f32 v[50:51], v[54:55], 0 op_sel_hi:[1,0]
	v_pk_add_f32 v[54:55], v[46:47], 0 op_sel_hi:[1,0]
	v_pk_add_f32 v[46:47], v[44:45], 0 op_sel_hi:[1,0]
	v_cvt_pk_bf16_f32 v44, v52, v53
	v_cvt_pk_bf16_f32 v45, v50, v51
	s_nop 0
	v_cvt_pk_bf16_f32 v46, v46, v47
	v_cvt_pk_bf16_f32 v47, v54, v55
	global_store_dwordx4 v[48:49], v[44:47], off sc0 sc1
	s_nop 1
	v_pk_add_f32 v[44:45], v[34:35], 0 op_sel_hi:[1,0]
	v_pk_add_f32 v[34:35], v[32:33], 0 op_sel_hi:[1,0]
	v_cvt_pk_bf16_f32 v32, v40, v41
	v_cvt_pk_bf16_f32 v33, v42, v43
	s_nop 0
	v_cvt_pk_bf16_f32 v34, v34, v35
	v_cvt_pk_bf16_f32 v35, v44, v45
	global_store_dwordx4 v[48:49], v[32:35], off offset:256 sc0 sc1
	s_nop 1
	v_add_u32_e32 v32, 0xa0, v150
	v_mad_i64_i32 v[32:33], s[18:19], v32, s64, v[140:141]
	v_pk_add_f32 v[34:35], v[38:39], 0 op_sel_hi:[1,0]
	v_pk_add_f32 v[38:39], v[30:31], 0 op_sel_hi:[1,0]
	v_pk_add_f32 v[30:31], v[28:29], 0 op_sel_hi:[1,0]
	v_cvt_pk_bf16_f32 v28, v36, v37
	v_cvt_pk_bf16_f32 v29, v34, v35
	s_nop 0
	v_cvt_pk_bf16_f32 v30, v30, v31
	v_cvt_pk_bf16_f32 v31, v38, v39
	global_store_dwordx4 v[32:33], v[28:31], off sc0 sc1
	s_nop 1
	v_pk_add_f32 v[28:29], v[18:19], 0 op_sel_hi:[1,0]
	v_pk_add_f32 v[18:19], v[16:17], 0 op_sel_hi:[1,0]
	v_cvt_pk_bf16_f32 v16, v24, v25
	v_cvt_pk_bf16_f32 v17, v26, v27
	s_nop 0
	v_cvt_pk_bf16_f32 v18, v18, v19
	v_cvt_pk_bf16_f32 v19, v28, v29
	global_store_dwordx4 v[32:33], v[16:19], off offset:256 sc0 sc1
	s_nop 1
	v_add_u32_e32 v16, 0xb0, v150
	v_mad_i64_i32 v[16:17], s[18:19], v16, s64, v[140:141]
	v_pk_add_f32 v[18:19], v[22:23], 0 op_sel_hi:[1,0]
	v_pk_add_f32 v[22:23], v[14:15], 0 op_sel_hi:[1,0]
	v_pk_add_f32 v[14:15], v[12:13], 0 op_sel_hi:[1,0]
	v_cvt_pk_bf16_f32 v12, v20, v21
	v_cvt_pk_bf16_f32 v13, v18, v19
	s_mov_b64 s[18:19], s[10:11]
	v_cvt_pk_bf16_f32 v14, v14, v15
	v_cvt_pk_bf16_f32 v15, v22, v23
	global_store_dwordx4 v[16:17], v[12:15], off sc0 sc1
	s_nop 1
	v_pk_add_f32 v[12:13], v[6:7], 0 op_sel_hi:[1,0]
	v_pk_add_f32 v[6:7], v[4:5], 0 op_sel_hi:[1,0]
	v_cvt_pk_bf16_f32 v4, v8, v9
	v_cvt_pk_bf16_f32 v5, v10, v11
	s_nop 0
	v_cvt_pk_bf16_f32 v6, v6, v7
	v_cvt_pk_bf16_f32 v7, v12, v13
	global_store_dwordx4 v[16:17], v[4:7], off offset:256 sc0 sc1
	s_cbranch_vccz .LBB0_160
	s_waitcnt vmcnt(0)
	s_cmpk_gt_u32 s24, 0xff
	s_cbranch_scc1 .LBB0_170
	s_barrier
